# SwiGLU GEMM epilogue stores write-through (sc1), 16-byte stores only
# baseline (speedup 1.0000x reference)
; __device__ __forceinline__ unsigned cvtpk(float lo, float hi) { f32x2_t v = {lo, hi}; bf16x2_t b = __builtin_convertvector(v, bf16x2_t); return __builtin_bit_cast(unsigned, b); }
;     __device__ __forceinline__ void operator()(const f32x4 (&acc)[2][2][4][2], const Unit& u, int wr, int wc, int fr, int fq, const float (&pre)[8]) const {
;         const int row0 = u.pm * 256 + wr * 64 + fr, col0 = u.pn * 128 + wc * 32 + 8 * fq;
; #pragma unroll
;         for (int ai = 0; ai < 2; ++ai)
; #pragma unroll
;             for (int m = 0; m < 4; ++m) { bf16_t* rowp = O + (size_t)(row0 + ai * 128 + m * 16) * ldc + col0; const float r = rsqrtf(pre[ai * 4 + m] * (1.f / 1024.f) + 1e-6f);
;                 const float k1 = r * -1.4426950408889634f, rr = r * r; u32x4 w;
; #pragma unroll
;                 for (int n = 0; n < 2; ++n) { const f32x4 g = acc[ai][0][m][n], uu = acc[ai][1][m][n]; const f32x4 t = g * uu, x = g * k1; f32x4 d;
;                     d[0] = __builtin_amdgcn_exp2f(x[0]); d[1] = __builtin_amdgcn_exp2f(x[1]); d[2] = __builtin_amdgcn_exp2f(x[2]); d[3] = __builtin_amdgcn_exp2f(x[3]);
;                     d = d + 1.0f;
;                     d[0] = __builtin_amdgcn_rcpf(d[0]); d[1] = __builtin_amdgcn_rcpf(d[1]); d[2] = __builtin_amdgcn_rcpf(d[2]); d[3] = __builtin_amdgcn_rcpf(d[3]);
;                     const f32x4 o = (t * d) * rr;
;                     if (n == 0) { w.x = cvtpk(o[0], o[1]); w.y = cvtpk(o[2], o[3]); } else { w.z = cvtpk(o[0], o[1]); w.w = cvtpk(o[2], o[3]); } }
;                 *(u32x4*)rowp = w; }
.LBB0_183:
	s_waitcnt vmcnt(8)
	v_fmamk_f32 v153, v153, 0x3a800000, v189
	v_cmp_gt_f32_e32 vcc, s27, v153
	v_mul_f32_e32 v155, 0x4b800000, v153
	v_pk_mul_f32 v[124:125], v[128:129], v[124:125]
	v_cndmask_b32_e32 v153, v153, v155, vcc
	v_rsq_f32_e32 v153, v153
	v_pk_mul_f32 v[122:123], v[126:127], v[122:123]
	v_pk_mul_f32 v[116:117], v[120:121], v[116:117]
	v_pk_mul_f32 v[114:115], v[118:119], v[114:115]
	v_mul_f32_e32 v155, 0x45800000, v153
	v_cndmask_b32_e32 v153, v153, v155, vcc
	v_mul_f32_e32 v156, 0xbfb8aa3b, v153
	v_pk_mul_f32 v[128:129], v[156:157], v[128:129] op_sel_hi:[0,1]
	v_pk_mul_f32 v[126:127], v[156:157], v[126:127] op_sel_hi:[0,1]
	v_pk_mul_f32 v[120:121], v[156:157], v[120:121] op_sel_hi:[0,1]
	v_pk_mul_f32 v[118:119], v[156:157], v[118:119] op_sel_hi:[0,1]
	v_exp_f32_e32 v126, v126
	v_exp_f32_e32 v127, v127
	v_exp_f32_e32 v128, v128
	v_exp_f32_e32 v129, v129
	v_exp_f32_e32 v118, v118
	v_exp_f32_e32 v119, v119
	v_exp_f32_e32 v120, v120
	v_exp_f32_e32 v121, v121
	v_pk_add_f32 v[128:129], v[128:129], 1.0 op_sel_hi:[1,0]
	v_pk_add_f32 v[126:127], v[126:127], 1.0 op_sel_hi:[1,0]
	v_pk_add_f32 v[118:119], v[118:119], 1.0 op_sel_hi:[1,0]
	v_pk_add_f32 v[120:121], v[120:121], 1.0 op_sel_hi:[1,0]
	v_rcp_f32_e32 v126, v126
	v_rcp_f32_e32 v127, v127
	v_rcp_f32_e32 v128, v128
	v_rcp_f32_e32 v129, v129
	v_rcp_f32_e32 v118, v118
	v_rcp_f32_e32 v119, v119
	v_rcp_f32_e32 v120, v120
	v_rcp_f32_e32 v121, v121
	v_lshl_or_b32 v140, s24, 7, v145
	v_readlane_b32 s14, v252, 20
	v_ashrrev_i32_e32 v141, 31, v140
	v_readlane_b32 s15, v252, 21
	v_mul_f32_e32 v158, v153, v153
	v_pk_mul_f32 v[122:123], v[126:127], v[122:123]
	v_pk_mul_f32 v[124:125], v[128:129], v[124:125]
	v_pk_mul_f32 v[114:115], v[118:119], v[114:115]
	v_pk_mul_f32 v[116:117], v[120:121], v[116:117]
	v_lshl_add_u32 v154, s3, 8, v142
	v_lshl_add_u64 v[140:141], v[140:141], 1, s[14:15]
	v_pk_mul_f32 v[124:125], v[158:159], v[124:125] op_sel_hi:[0,1]
	v_pk_mul_f32 v[122:123], v[158:159], v[122:123] op_sel_hi:[0,1]
	v_pk_mul_f32 v[116:117], v[158:159], v[116:117] op_sel_hi:[0,1]
	v_pk_mul_f32 v[114:115], v[158:159], v[114:115] op_sel_hi:[0,1]
	v_cvt_pk_bf16_f32 v122, v122, v123
	v_cvt_pk_bf16_f32 v123, v124, v125
	v_cvt_pk_bf16_f32 v124, v114, v115
	v_cvt_pk_bf16_f32 v125, v116, v117
	v_mad_i64_i32 v[114:115], s[14:15], v154, s45, v[140:141]
	global_store_dwordx4 v[114:115], v[122:125], off sc1
	v_fmamk_f32 v114, v152, 0x3a800000, v189
	v_cmp_gt_f32_e32 vcc, s27, v114
	v_mul_f32_e32 v116, 0x4b800000, v114
	v_or_b32_e32 v115, 16, v154
	v_cndmask_b32_e32 v114, v114, v116, vcc
	v_rsq_f32_e32 v114, v114
	v_pk_mul_f32 v[108:109], v[112:113], v[108:109]
	v_pk_mul_f32 v[106:107], v[110:111], v[106:107]
	v_pk_mul_f32 v[100:101], v[104:105], v[100:101]
	v_mul_f32_e32 v116, 0x45800000, v114
	v_cndmask_b32_e32 v116, v114, v116, vcc
	v_mul_f32_e32 v114, 0xbfb8aa3b, v116
	v_pk_mul_f32 v[112:113], v[114:115], v[112:113] op_sel_hi:[0,1]
	v_pk_mul_f32 v[110:111], v[114:115], v[110:111] op_sel_hi:[0,1]
	v_pk_mul_f32 v[98:99], v[102:103], v[98:99]
	v_pk_mul_f32 v[104:105], v[114:115], v[104:105] op_sel_hi:[0,1]
	v_pk_mul_f32 v[102:103], v[114:115], v[102:103] op_sel_hi:[0,1]
	v_exp_f32_e32 v110, v110
	v_exp_f32_e32 v111, v111
	v_exp_f32_e32 v112, v112
	v_exp_f32_e32 v113, v113
	v_exp_f32_e32 v102, v102
	v_exp_f32_e32 v103, v103
	v_exp_f32_e32 v104, v104
	v_exp_f32_e32 v105, v105
	v_pk_add_f32 v[112:113], v[112:113], 1.0 op_sel_hi:[1,0]
	v_pk_add_f32 v[110:111], v[110:111], 1.0 op_sel_hi:[1,0]
	v_pk_add_f32 v[102:103], v[102:103], 1.0 op_sel_hi:[1,0]
	v_pk_add_f32 v[104:105], v[104:105], 1.0 op_sel_hi:[1,0]
	v_rcp_f32_e32 v110, v110
	v_rcp_f32_e32 v111, v111
	v_rcp_f32_e32 v112, v112
	v_rcp_f32_e32 v113, v113
	v_rcp_f32_e32 v102, v102
	v_rcp_f32_e32 v103, v103
	v_rcp_f32_e32 v104, v104
	v_rcp_f32_e32 v105, v105
	v_mul_f32_e32 v116, v116, v116
	v_pk_mul_f32 v[106:107], v[110:111], v[106:107]
	v_pk_mul_f32 v[108:109], v[112:113], v[108:109]
	v_pk_mul_f32 v[98:99], v[102:103], v[98:99]
	v_pk_mul_f32 v[100:101], v[104:105], v[100:101]
	v_pk_mul_f32 v[108:109], v[116:117], v[108:109] op_sel_hi:[0,1]
	v_pk_mul_f32 v[106:107], v[116:117], v[106:107] op_sel_hi:[0,1]
	v_pk_mul_f32 v[100:101], v[116:117], v[100:101] op_sel_hi:[0,1]
	v_pk_mul_f32 v[98:99], v[116:117], v[98:99] op_sel_hi:[0,1]
	v_cvt_pk_bf16_f32 v106, v106, v107
	v_cvt_pk_bf16_f32 v107, v108, v109
	v_cvt_pk_bf16_f32 v108, v98, v99
	v_cvt_pk_bf16_f32 v109, v100, v101
	v_mad_i64_i32 v[98:99], s[14:15], v115, s45, v[140:141]
	global_store_dwordx4 v[98:99], v[106:109], off sc1
	v_fmamk_f32 v98, v151, 0x3a800000, v189
	v_cmp_gt_f32_e32 vcc, s27, v98
	v_mul_f32_e32 v100, 0x4b800000, v98
	v_or_b32_e32 v99, 32, v154
	v_cndmask_b32_e32 v98, v98, v100, vcc
	v_rsq_f32_e32 v98, v98
	v_pk_mul_f32 v[92:93], v[96:97], v[92:93]
	v_pk_mul_f32 v[90:91], v[94:95], v[90:91]
	v_pk_mul_f32 v[84:85], v[88:89], v[84:85]
	v_mul_f32_e32 v100, 0x45800000, v98
	v_cndmask_b32_e32 v100, v98, v100, vcc
	v_mul_f32_e32 v98, 0xbfb8aa3b, v100
	v_pk_mul_f32 v[96:97], v[98:99], v[96:97] op_sel_hi:[0,1]
	v_pk_mul_f32 v[94:95], v[98:99], v[94:95] op_sel_hi:[0,1]
	v_pk_mul_f32 v[82:83], v[86:87], v[82:83]
	v_pk_mul_f32 v[88:89], v[98:99], v[88:89] op_sel_hi:[0,1]
	v_pk_mul_f32 v[86:87], v[98:99], v[86:87] op_sel_hi:[0,1]
	v_exp_f32_e32 v94, v94
	v_exp_f32_e32 v95, v95
	v_exp_f32_e32 v96, v96
	v_exp_f32_e32 v97, v97
	v_exp_f32_e32 v86, v86
	v_exp_f32_e32 v87, v87
	v_exp_f32_e32 v88, v88
	v_exp_f32_e32 v89, v89
	v_pk_add_f32 v[96:97], v[96:97], 1.0 op_sel_hi:[1,0]
	v_pk_add_f32 v[94:95], v[94:95], 1.0 op_sel_hi:[1,0]
	v_pk_add_f32 v[86:87], v[86:87], 1.0 op_sel_hi:[1,0]
; __device__ __forceinline__ unsigned cvtpk(float lo, float hi) { f32x2_t v = {lo, hi}; bf16x2_t b = __builtin_convertvector(v, bf16x2_t); return __builtin_bit_cast(unsigned, b); }
;     __device__ __forceinline__ void operator()(const f32x4 (&acc)[2][2][4][2], const Unit& u, int wr, int wc, int fr, int fq, const float (&pre)[8]) const {
;     ...
;         for (int ai = 0; ai < 2; ++ai)
; #pragma unroll
;             for (int m = 0; m < 4; ++m) { bf16_t* rowp = O + (size_t)(row0 + ai * 128 + m * 16) * ldc + col0; const float r = rsqrtf(pre[ai * 4 + m] * (1.f / 1024.f) + 1e-6f);
;                 const float k1 = r * -1.4426950408889634f, rr = r * r; u32x4 w;
; #pragma unroll
;                 for (int n = 0; n < 2; ++n) { const f32x4 g = acc[ai][0][m][n], uu = acc[ai][1][m][n]; const f32x4 t = g * uu, x = g * k1; f32x4 d;
;                     d[0] = __builtin_amdgcn_exp2f(x[0]); d[1] = __builtin_amdgcn_exp2f(x[1]); d[2] = __builtin_amdgcn_exp2f(x[2]); d[3] = __builtin_amdgcn_exp2f(x[3]);
;                     d = d + 1.0f;
;                     d[0] = __builtin_amdgcn_rcpf(d[0]); d[1] = __builtin_amdgcn_rcpf(d[1]); d[2] = __builtin_amdgcn_rcpf(d[2]); d[3] = __builtin_amdgcn_rcpf(d[3]);
;                     const f32x4 o = (t * d) * rr;
;                     if (n == 0) { w.x = cvtpk(o[0], o[1]); w.y = cvtpk(o[2], o[3]); } else { w.z = cvtpk(o[0], o[1]); w.w = cvtpk(o[2], o[3]); } }
;                 *(u32x4*)rowp = w; }
	v_pk_add_f32 v[88:89], v[88:89], 1.0 op_sel_hi:[1,0]
	v_rcp_f32_e32 v94, v94
	v_rcp_f32_e32 v95, v95
	v_rcp_f32_e32 v96, v96
	v_rcp_f32_e32 v97, v97
	v_rcp_f32_e32 v86, v86
	v_rcp_f32_e32 v87, v87
	v_rcp_f32_e32 v88, v88
	v_rcp_f32_e32 v89, v89
	v_mul_f32_e32 v100, v100, v100
	v_pk_mul_f32 v[90:91], v[94:95], v[90:91]
	v_pk_mul_f32 v[92:93], v[96:97], v[92:93]
	v_pk_mul_f32 v[82:83], v[86:87], v[82:83]
	v_pk_mul_f32 v[84:85], v[88:89], v[84:85]
	v_pk_mul_f32 v[92:93], v[100:101], v[92:93] op_sel_hi:[0,1]
	v_pk_mul_f32 v[90:91], v[100:101], v[90:91] op_sel_hi:[0,1]
	v_pk_mul_f32 v[84:85], v[100:101], v[84:85] op_sel_hi:[0,1]
	v_pk_mul_f32 v[82:83], v[100:101], v[82:83] op_sel_hi:[0,1]
	v_cvt_pk_bf16_f32 v90, v90, v91
	v_cvt_pk_bf16_f32 v91, v92, v93
	v_cvt_pk_bf16_f32 v92, v82, v83
	v_cvt_pk_bf16_f32 v93, v84, v85
	v_mad_i64_i32 v[82:83], s[14:15], v99, s45, v[140:141]
	global_store_dwordx4 v[82:83], v[90:93], off sc1
	v_fmamk_f32 v82, v150, 0x3a800000, v189
	v_cmp_gt_f32_e32 vcc, s27, v82
	v_mul_f32_e32 v84, 0x4b800000, v82
	v_or_b32_e32 v83, 48, v154
	v_cndmask_b32_e32 v82, v82, v84, vcc
	v_rsq_f32_e32 v82, v82
	v_pk_mul_f32 v[76:77], v[80:81], v[76:77]
	v_pk_mul_f32 v[74:75], v[78:79], v[74:75]
	v_pk_mul_f32 v[68:69], v[72:73], v[68:69]
	v_mul_f32_e32 v84, 0x45800000, v82
	v_cndmask_b32_e32 v84, v82, v84, vcc
	v_mul_f32_e32 v82, 0xbfb8aa3b, v84
	v_pk_mul_f32 v[80:81], v[82:83], v[80:81] op_sel_hi:[0,1]
	v_pk_mul_f32 v[78:79], v[82:83], v[78:79] op_sel_hi:[0,1]
	v_pk_mul_f32 v[66:67], v[70:71], v[66:67]
	v_pk_mul_f32 v[72:73], v[82:83], v[72:73] op_sel_hi:[0,1]
	v_pk_mul_f32 v[70:71], v[82:83], v[70:71] op_sel_hi:[0,1]
	v_exp_f32_e32 v78, v78
	v_exp_f32_e32 v79, v79
	v_exp_f32_e32 v80, v80
	v_exp_f32_e32 v81, v81
	v_exp_f32_e32 v70, v70
	v_exp_f32_e32 v71, v71
	v_exp_f32_e32 v72, v72
	v_exp_f32_e32 v73, v73
	v_pk_add_f32 v[80:81], v[80:81], 1.0 op_sel_hi:[1,0]
	v_pk_add_f32 v[78:79], v[78:79], 1.0 op_sel_hi:[1,0]
	v_pk_add_f32 v[70:71], v[70:71], 1.0 op_sel_hi:[1,0]
	v_pk_add_f32 v[72:73], v[72:73], 1.0 op_sel_hi:[1,0]
	v_rcp_f32_e32 v78, v78
	v_rcp_f32_e32 v79, v79
	v_rcp_f32_e32 v80, v80
	v_rcp_f32_e32 v81, v81
	v_rcp_f32_e32 v70, v70
	v_rcp_f32_e32 v71, v71
	v_rcp_f32_e32 v72, v72
	v_rcp_f32_e32 v73, v73
	v_mul_f32_e32 v84, v84, v84
	v_pk_mul_f32 v[74:75], v[78:79], v[74:75]
	v_pk_mul_f32 v[76:77], v[80:81], v[76:77]
	v_pk_mul_f32 v[66:67], v[70:71], v[66:67]
	v_pk_mul_f32 v[68:69], v[72:73], v[68:69]
	v_pk_mul_f32 v[76:77], v[84:85], v[76:77] op_sel_hi:[0,1]
	v_pk_mul_f32 v[74:75], v[84:85], v[74:75] op_sel_hi:[0,1]
	v_pk_mul_f32 v[68:69], v[84:85], v[68:69] op_sel_hi:[0,1]
	v_pk_mul_f32 v[66:67], v[84:85], v[66:67] op_sel_hi:[0,1]
	v_cvt_pk_bf16_f32 v74, v74, v75
	v_cvt_pk_bf16_f32 v75, v76, v77
	v_cvt_pk_bf16_f32 v76, v66, v67
	v_cvt_pk_bf16_f32 v77, v68, v69
	v_mad_i64_i32 v[66:67], s[14:15], v83, s45, v[140:141]
	global_store_dwordx4 v[66:67], v[74:77], off sc1
	v_fmamk_f32 v66, v149, 0x3a800000, v189
	v_cmp_gt_f32_e32 vcc, s27, v66
	v_mul_f32_e32 v68, 0x4b800000, v66
	v_add_u32_e32 v67, 0x80, v154
	v_cndmask_b32_e32 v66, v66, v68, vcc
	v_rsq_f32_e32 v66, v66
	v_pk_mul_f32 v[60:61], v[64:65], v[60:61]
	v_pk_mul_f32 v[58:59], v[62:63], v[58:59]
	v_pk_mul_f32 v[52:53], v[56:57], v[52:53]
	v_mul_f32_e32 v68, 0x45800000, v66
	v_cndmask_b32_e32 v68, v66, v68, vcc
	v_mul_f32_e32 v66, 0xbfb8aa3b, v68
	v_pk_mul_f32 v[64:65], v[66:67], v[64:65] op_sel_hi:[0,1]
	v_pk_mul_f32 v[62:63], v[66:67], v[62:63] op_sel_hi:[0,1]
	v_pk_mul_f32 v[50:51], v[54:55], v[50:51]
	v_pk_mul_f32 v[56:57], v[66:67], v[56:57] op_sel_hi:[0,1]
	v_pk_mul_f32 v[54:55], v[66:67], v[54:55] op_sel_hi:[0,1]
	v_exp_f32_e32 v62, v62
	v_exp_f32_e32 v63, v63
	v_exp_f32_e32 v64, v64
	v_exp_f32_e32 v65, v65
	v_exp_f32_e32 v54, v54
	v_exp_f32_e32 v55, v55
	v_exp_f32_e32 v56, v56
	v_exp_f32_e32 v57, v57
	v_pk_add_f32 v[64:65], v[64:65], 1.0 op_sel_hi:[1,0]
	v_pk_add_f32 v[62:63], v[62:63], 1.0 op_sel_hi:[1,0]
	v_pk_add_f32 v[54:55], v[54:55], 1.0 op_sel_hi:[1,0]
	v_pk_add_f32 v[56:57], v[56:57], 1.0 op_sel_hi:[1,0]
	v_rcp_f32_e32 v62, v62
	v_rcp_f32_e32 v63, v63
	v_rcp_f32_e32 v64, v64
	v_rcp_f32_e32 v65, v65
	v_rcp_f32_e32 v54, v54
	v_rcp_f32_e32 v55, v55
	v_rcp_f32_e32 v56, v56
	v_rcp_f32_e32 v57, v57
	v_mul_f32_e32 v68, v68, v68
	v_pk_mul_f32 v[58:59], v[62:63], v[58:59]
	v_pk_mul_f32 v[60:61], v[64:65], v[60:61]
	v_pk_mul_f32 v[50:51], v[54:55], v[50:51]
	v_pk_mul_f32 v[52:53], v[56:57], v[52:53]
	v_pk_mul_f32 v[60:61], v[68:69], v[60:61] op_sel_hi:[0,1]
	v_pk_mul_f32 v[58:59], v[68:69], v[58:59] op_sel_hi:[0,1]
	v_pk_mul_f32 v[52:53], v[68:69], v[52:53] op_sel_hi:[0,1]
	v_pk_mul_f32 v[50:51], v[68:69], v[50:51] op_sel_hi:[0,1]
	v_cvt_pk_bf16_f32 v58, v58, v59
	v_cvt_pk_bf16_f32 v59, v60, v61
	v_cvt_pk_bf16_f32 v60, v50, v51
	v_cvt_pk_bf16_f32 v61, v52, v53
	v_mad_i64_i32 v[50:51], s[14:15], v67, s45, v[140:141]
	global_store_dwordx4 v[50:51], v[58:61], off sc1
	v_fmamk_f32 v50, v148, 0x3a800000, v189
	v_cmp_gt_f32_e32 vcc, s27, v50
	v_mul_f32_e32 v52, 0x4b800000, v50
	v_add_u32_e32 v51, 0x90, v154
	v_cndmask_b32_e32 v50, v50, v52, vcc
	v_rsq_f32_e32 v50, v50
	v_pk_mul_f32 v[44:45], v[48:49], v[44:45]
	v_pk_mul_f32 v[42:43], v[46:47], v[42:43]
	v_pk_mul_f32 v[36:37], v[40:41], v[36:37]
	v_mul_f32_e32 v52, 0x45800000, v50
	v_cndmask_b32_e32 v52, v50, v52, vcc
	v_mul_f32_e32 v50, 0xbfb8aa3b, v52
	v_pk_mul_f32 v[48:49], v[50:51], v[48:49] op_sel_hi:[0,1]
	v_pk_mul_f32 v[46:47], v[50:51], v[46:47] op_sel_hi:[0,1]
	v_pk_mul_f32 v[34:35], v[38:39], v[34:35]
	v_pk_mul_f32 v[40:41], v[50:51], v[40:41] op_sel_hi:[0,1]
	v_pk_mul_f32 v[38:39], v[50:51], v[38:39] op_sel_hi:[0,1]
; __device__ __forceinline__ unsigned cvtpk(float lo, float hi) { f32x2_t v = {lo, hi}; bf16x2_t b = __builtin_convertvector(v, bf16x2_t); return __builtin_bit_cast(unsigned, b); }
;     __device__ __forceinline__ void prefetch(const Unit& u, int wr, int fr, float (&pre)[8]) const {
;         const int row0 = u.pm * 256 + wr * 64 + fr;
; #pragma unroll
;         for (int i = 0; i < 8; ++i) pre[i] = RS[row0 + (i >> 2) * 128 + (i & 3) * 16];
;     }
;     __device__ __forceinline__ void operator()(const f32x4 (&acc)[2][2][4][2], const Unit& u, int wr, int wc, int fr, int fq, const float (&pre)[8]) const {
;     ...
;         for (int ai = 0; ai < 2; ++ai)
; #pragma unroll
;             for (int m = 0; m < 4; ++m) { bf16_t* rowp = O + (size_t)(row0 + ai * 128 + m * 16) * ldc + col0; const float r = rsqrtf(pre[ai * 4 + m] * (1.f / 1024.f) + 1e-6f);
;                 const float k1 = r * -1.4426950408889634f, rr = r * r; u32x4 w;
; #pragma unroll
;                 for (int n = 0; n < 2; ++n) { const f32x4 g = acc[ai][0][m][n], uu = acc[ai][1][m][n]; const f32x4 t = g * uu, x = g * k1; f32x4 d;
;                     d[0] = __builtin_amdgcn_exp2f(x[0]); d[1] = __builtin_amdgcn_exp2f(x[1]); d[2] = __builtin_amdgcn_exp2f(x[2]); d[3] = __builtin_amdgcn_exp2f(x[3]);
;                     d = d + 1.0f;
;                     d[0] = __builtin_amdgcn_rcpf(d[0]); d[1] = __builtin_amdgcn_rcpf(d[1]); d[2] = __builtin_amdgcn_rcpf(d[2]); d[3] = __builtin_amdgcn_rcpf(d[3]);
;                     const f32x4 o = (t * d) * rr;
;                     if (n == 0) { w.x = cvtpk(o[0], o[1]); w.y = cvtpk(o[2], o[3]); } else { w.z = cvtpk(o[0], o[1]); w.w = cvtpk(o[2], o[3]); } }
;                 *(u32x4*)rowp = w; }
	v_exp_f32_e32 v46, v46
	v_exp_f32_e32 v47, v47
	v_exp_f32_e32 v48, v48
	v_exp_f32_e32 v49, v49
	v_exp_f32_e32 v38, v38
	v_exp_f32_e32 v39, v39
	v_exp_f32_e32 v40, v40
	v_exp_f32_e32 v41, v41
	v_pk_add_f32 v[48:49], v[48:49], 1.0 op_sel_hi:[1,0]
	v_pk_add_f32 v[46:47], v[46:47], 1.0 op_sel_hi:[1,0]
	v_pk_add_f32 v[38:39], v[38:39], 1.0 op_sel_hi:[1,0]
	v_pk_add_f32 v[40:41], v[40:41], 1.0 op_sel_hi:[1,0]
	v_rcp_f32_e32 v46, v46
	v_rcp_f32_e32 v47, v47
	v_rcp_f32_e32 v48, v48
	v_rcp_f32_e32 v49, v49
	v_rcp_f32_e32 v38, v38
	v_rcp_f32_e32 v39, v39
	v_rcp_f32_e32 v40, v40
	v_rcp_f32_e32 v41, v41
	v_mul_f32_e32 v52, v52, v52
	v_pk_mul_f32 v[42:43], v[46:47], v[42:43]
	v_pk_mul_f32 v[44:45], v[48:49], v[44:45]
	v_pk_mul_f32 v[34:35], v[38:39], v[34:35]
	v_pk_mul_f32 v[36:37], v[40:41], v[36:37]
	v_pk_mul_f32 v[44:45], v[52:53], v[44:45] op_sel_hi:[0,1]
	v_pk_mul_f32 v[42:43], v[52:53], v[42:43] op_sel_hi:[0,1]
	v_pk_mul_f32 v[36:37], v[52:53], v[36:37] op_sel_hi:[0,1]
	v_pk_mul_f32 v[34:35], v[52:53], v[34:35] op_sel_hi:[0,1]
	v_cvt_pk_bf16_f32 v42, v42, v43
	v_cvt_pk_bf16_f32 v43, v44, v45
	v_cvt_pk_bf16_f32 v44, v34, v35
	v_cvt_pk_bf16_f32 v45, v36, v37
	v_mad_i64_i32 v[34:35], s[14:15], v51, s45, v[140:141]
	global_store_dwordx4 v[34:35], v[42:45], off sc1
	v_fmamk_f32 v34, v147, 0x3a800000, v189
	v_cmp_gt_f32_e32 vcc, s27, v34
	v_mul_f32_e32 v36, 0x4b800000, v34
	v_add_u32_e32 v35, 0xa0, v154
	v_cndmask_b32_e32 v34, v34, v36, vcc
	v_rsq_f32_e32 v34, v34
	v_pk_mul_f32 v[28:29], v[32:33], v[28:29]
	v_pk_mul_f32 v[26:27], v[30:31], v[26:27]
	v_pk_mul_f32 v[20:21], v[24:25], v[20:21]
	v_mul_f32_e32 v36, 0x45800000, v34
	v_cndmask_b32_e32 v36, v34, v36, vcc
	v_mul_f32_e32 v34, 0xbfb8aa3b, v36
	v_pk_mul_f32 v[32:33], v[34:35], v[32:33] op_sel_hi:[0,1]
	v_pk_mul_f32 v[30:31], v[34:35], v[30:31] op_sel_hi:[0,1]
	v_pk_mul_f32 v[18:19], v[22:23], v[18:19]
	v_pk_mul_f32 v[24:25], v[34:35], v[24:25] op_sel_hi:[0,1]
	v_pk_mul_f32 v[22:23], v[34:35], v[22:23] op_sel_hi:[0,1]
	v_exp_f32_e32 v30, v30
	v_exp_f32_e32 v31, v31
	v_exp_f32_e32 v32, v32
	v_exp_f32_e32 v33, v33
	v_exp_f32_e32 v22, v22
	v_exp_f32_e32 v23, v23
	v_exp_f32_e32 v24, v24
	v_exp_f32_e32 v25, v25
	v_pk_add_f32 v[32:33], v[32:33], 1.0 op_sel_hi:[1,0]
	v_pk_add_f32 v[30:31], v[30:31], 1.0 op_sel_hi:[1,0]
	v_pk_add_f32 v[22:23], v[22:23], 1.0 op_sel_hi:[1,0]
	v_pk_add_f32 v[24:25], v[24:25], 1.0 op_sel_hi:[1,0]
	v_rcp_f32_e32 v30, v30
	v_rcp_f32_e32 v31, v31
	v_rcp_f32_e32 v32, v32
	v_rcp_f32_e32 v33, v33
	v_rcp_f32_e32 v22, v22
	v_rcp_f32_e32 v23, v23
	v_rcp_f32_e32 v24, v24
	v_rcp_f32_e32 v25, v25
	v_mul_f32_e32 v36, v36, v36
	v_pk_mul_f32 v[26:27], v[30:31], v[26:27]
	v_pk_mul_f32 v[28:29], v[32:33], v[28:29]
	v_pk_mul_f32 v[18:19], v[22:23], v[18:19]
	v_pk_mul_f32 v[20:21], v[24:25], v[20:21]
	v_pk_mul_f32 v[28:29], v[36:37], v[28:29] op_sel_hi:[0,1]
	v_pk_mul_f32 v[26:27], v[36:37], v[26:27] op_sel_hi:[0,1]
	v_pk_mul_f32 v[20:21], v[36:37], v[20:21] op_sel_hi:[0,1]
	v_pk_mul_f32 v[18:19], v[36:37], v[18:19] op_sel_hi:[0,1]
	v_cvt_pk_bf16_f32 v26, v26, v27
	v_cvt_pk_bf16_f32 v27, v28, v29
	v_cvt_pk_bf16_f32 v28, v18, v19
	v_cvt_pk_bf16_f32 v29, v20, v21
	v_mad_i64_i32 v[18:19], s[14:15], v35, s45, v[140:141]
	global_store_dwordx4 v[18:19], v[26:29], off sc1
	v_fmamk_f32 v18, v144, 0x3a800000, v189
	v_cmp_gt_f32_e32 vcc, s27, v18
	v_mul_f32_e32 v19, 0x4b800000, v18
	v_pk_mul_f32 v[12:13], v[16:17], v[12:13]
	v_cndmask_b32_e32 v18, v18, v19, vcc
	v_rsq_f32_e32 v18, v18
	v_pk_mul_f32 v[10:11], v[14:15], v[10:11]
	v_pk_mul_f32 v[2:3], v[6:7], v[2:3]
	v_pk_mul_f32 v[4:5], v[8:9], v[4:5]
	v_mul_f32_e32 v19, 0x45800000, v18
	v_cndmask_b32_e32 v19, v18, v19, vcc
	v_mul_f32_e32 v20, 0xbfb8aa3b, v19
	v_pk_mul_f32 v[16:17], v[20:21], v[16:17] op_sel_hi:[0,1]
	v_pk_mul_f32 v[14:15], v[20:21], v[14:15] op_sel_hi:[0,1]
	v_pk_mul_f32 v[6:7], v[20:21], v[6:7] op_sel_hi:[0,1]
	v_exp_f32_e32 v14, v14
	v_exp_f32_e32 v15, v15
	v_exp_f32_e32 v16, v16
	v_exp_f32_e32 v17, v17
	v_pk_mul_f32 v[8:9], v[20:21], v[8:9] op_sel_hi:[0,1]
	v_exp_f32_e32 v6, v6
	v_exp_f32_e32 v7, v7
	v_exp_f32_e32 v8, v8
	v_exp_f32_e32 v9, v9
	v_pk_add_f32 v[16:17], v[16:17], 1.0 op_sel_hi:[1,0]
	v_pk_add_f32 v[14:15], v[14:15], 1.0 op_sel_hi:[1,0]
	v_pk_add_f32 v[6:7], v[6:7], 1.0 op_sel_hi:[1,0]
	v_rcp_f32_e32 v14, v14
	v_rcp_f32_e32 v15, v15
	v_rcp_f32_e32 v16, v16
	v_rcp_f32_e32 v17, v17
	v_pk_add_f32 v[8:9], v[8:9], 1.0 op_sel_hi:[1,0]
	v_rcp_f32_e32 v6, v6
	v_rcp_f32_e32 v7, v7
	v_rcp_f32_e32 v8, v8
	v_rcp_f32_e32 v9, v9
	v_mul_f32_e32 v18, v19, v19
	v_pk_mul_f32 v[10:11], v[14:15], v[10:11]
	v_pk_mul_f32 v[12:13], v[16:17], v[12:13]
	v_pk_mul_f32 v[2:3], v[6:7], v[2:3]
	v_pk_mul_f32 v[12:13], v[18:19], v[12:13] op_sel_hi:[0,1]
	v_pk_mul_f32 v[10:11], v[18:19], v[10:11] op_sel_hi:[0,1]
	v_pk_mul_f32 v[4:5], v[8:9], v[4:5]
	v_pk_mul_f32 v[2:3], v[18:19], v[2:3] op_sel_hi:[0,1]
	v_cvt_pk_bf16_f32 v10, v10, v11
	v_cvt_pk_bf16_f32 v11, v12, v13
	v_pk_mul_f32 v[4:5], v[18:19], v[4:5] op_sel_hi:[0,1]
	v_cvt_pk_bf16_f32 v12, v2, v3
	v_add_u32_e32 v2, 0xb0, v154
	v_cvt_pk_bf16_f32 v13, v4, v5
	v_mad_i64_i32 v[2:3], s[14:15], v2, s45, v[140:141]
	s_mov_b64 s[16:17], -1
	s_and_b64 vcc, exec, s[36:37]
	global_store_dwordx4 v[2:3], v[10:13], off sc1
	s_cbranch_vccnz .LBB0_172
	v_lshl_add_u32 v2, s82, 8, v142
	v_ashrrev_i32_e32 v3, 31, v2
	v_lshl_add_u64 v[2:3], v[2:3], 2, s[50:51]
	global_load_dword v153, v[2:3], off
	global_load_dword v152, v[2:3], off offset:64
	global_load_dword v151, v[2:3], off offset:128
	global_load_dword v150, v[2:3], off offset:192
	global_load_dword v149, v[2:3], off offset:512
	global_load_dword v148, v[2:3], off offset:576
	global_load_dword v147, v[2:3], off offset:640
	global_load_dword v144, v[2:3], off offset:704
	s_andn2_b64 vcc, exec, s[54:55]
	s_cbranch_vccnz .LBB0_171
	s_barrier
	s_branch .LBB0_171
